# final RMSNorm: loop-invariant gain chunks loaded once before the loop (no load+wait behind every store)
# speedup vs baseline: 1.0049x; 1.0049x over previous
; DEV int get_tid() { int t; asm volatile("v_mov_b32 %0, %1" : "=v"(t) : "v"((int)(threadIdx.x & 255))); return t; }
; DEV int vbid() { return (int)blockIdx.x * 2 + vbsel(); }
; DEV int vgrid() { return (int)gridDim.x * 2; }
; DEV float bflo(unsigned w) { return __uint_as_float(w << 16); }
; DEV float bfhi(unsigned w) { return __uint_as_float(w & 0xffff0000u); }
; DEV void ph_final(const P& p) {
;   const int lane = get_tid() & 63, wid = get_tid() >> 6;
;   for (int item = vbid(); item < MLAT / 8; item += vgrid()) {
;     const int row0 = item * 8 + wid * 2;
;     f32x4 v[2][4]; float ss[2];
; #pragma unroll
;     for (int q = 0; q < 2; ++q)
; #pragma unroll
;       for (int i = 0; i < 4; ++i) { const u32x2 w = ((const u32x2*)((const bf16_t*)(p.ws + OFF_XN) + (size_t)(row0 + q) * 1024))[lane + 64 * i]; v[q][i] = (f32x4){bflo(w.x), bfhi(w.x), bflo(w.y), bfhi(w.y)}; }
; #pragma unroll
;     for (int q = 0; q < 2; ++q) {
;       float s = 0.f;
; #pragma unroll
;       for (int i = 0; i < 4; ++i) s += v[q][i][0] * v[q][i][0] + v[q][i][1] * v[q][i][1] + v[q][i][2] * v[q][i][2] + v[q][i][3] * v[q][i][3];
;       ss[q] = wave_sum(s);
;     }
.LBB0_1251:
	v_readfirstlane_b32 s0, v201
	s_lshr_b32 s0, s0, 8
	v_readlane_b32 s1, v253, 2
	s_add_i32 s1, s0, s1
	s_cmpk_gt_i32 s1, 0xfff
	v_mov_b32 v0, v238
	v_mov_b32 v1, v238
	s_cbranch_scc1 .LBB0_1254
	v_and_b32_e32 v8, 63, v0
	v_ashrrev_i32_e32 v0, 5, v1
	v_and_b32_e32 v12, -2, v0
	v_and_b32_e32 v0, 64, v237
	v_add_u32_e32 v0, 64, v0
	v_xor_b32_e32 v1, 32, v237
	v_cmp_lt_i32_e32 vcc, v1, v0
	s_load_dwordx4 s[4:7], s[88:89], 0xe0
	s_load_dwordx2 s[2:3], s[88:89], 0xf0
	v_cndmask_b32_e32 v1, v237, v1, vcc
	v_lshlrev_b32_e32 v15, 2, v1
	v_xor_b32_e32 v1, 16, v237
	v_cmp_lt_i32_e32 vcc, v1, v0
	v_mov_b32_e32 v11, 0
	v_lshlrev_b32_e32 v10, 4, v8
	v_cndmask_b32_e32 v1, v237, v1, vcc
	v_lshlrev_b32_e32 v22, 2, v1
	v_xor_b32_e32 v1, 8, v237
	v_cmp_lt_i32_e32 vcc, v1, v0
	v_lshlrev_b32_e32 v8, 3, v8
	v_mov_b32_e32 v9, v11
	v_cndmask_b32_e32 v1, v237, v1, vcc
	v_lshlrev_b32_e32 v23, 2, v1
	v_xor_b32_e32 v1, 4, v237
	v_cmp_lt_i32_e32 vcc, v1, v0
	s_waitcnt lgkmcnt(0)
	v_lshl_add_u64 v[8:9], s[2:3], 0, v[8:9]
	s_mov_b64 s[2:3], 0x5dcd000
	v_cndmask_b32_e32 v1, v237, v1, vcc
	v_lshlrev_b32_e32 v24, 2, v1
	v_xor_b32_e32 v1, 2, v237
	v_cmp_lt_i32_e32 vcc, v1, v0
	v_lshl_add_u64 v[8:9], v[8:9], 0, s[2:3]
	s_lshl_b32 s0, s0, 3
	v_cndmask_b32_e32 v1, v237, v1, vcc
	v_lshlrev_b32_e32 v25, 2, v1
	v_xor_b32_e32 v1, 1, v237
	v_cmp_lt_i32_e32 vcc, v1, v0
	v_readlane_b32 s2, v254, 23
	v_or_b32_e32 v2, 0x400, v10
	v_cndmask_b32_e32 v0, v237, v1, vcc
	v_mov_b32_e32 v3, v11
	v_or_b32_e32 v4, 0x800, v10
	v_mov_b32_e32 v5, v11
	v_or_b32_e32 v6, 0xc00, v10
	v_mov_b32_e32 v7, v11
	s_add_i32 s0, s2, s0
	v_lshlrev_b32_e32 v26, 2, v0
	v_lshl_add_u64 v[0:1], s[4:5], 0, v[10:11]
	v_lshl_add_u64 v[2:3], s[4:5], 0, v[2:3]
	v_lshl_add_u64 v[4:5], s[4:5], 0, v[4:5]
	v_lshl_add_u64 v[6:7], s[4:5], 0, v[6:7]
	v_lshl_add_u64 v[10:11], s[6:7], 0, v[10:11]
	v_add_u32_e32 v12, s0, v12
	s_mov_b32 s0, 0x3a800000
	v_mov_b32_e32 v14, 0x358637bd
	s_mov_b32 s2, 0x800000
	v_readlane_b32 s3, v254, 24
	global_load_dwordx4 v[72:75], v[0:1], off
	global_load_dwordx4 v[76:79], v[2:3], off
	global_load_dwordx4 v[80:83], v[4:5], off
	global_load_dwordx4 v[84:87], v[6:7], off
.LBB0_1253:
	v_ashrrev_i32_e32 v13, 31, v12
	v_lshlrev_b64 v[16:17], 11, v[12:13]
	v_lshl_add_u64 v[16:17], v[8:9], 0, v[16:17]
	global_load_dwordx2 v[18:19], v[16:17], off offset:512
	global_load_dwordx2 v[20:21], v[16:17], off
	global_load_dwordx2 v[32:33], v[16:17], off offset:1536
	global_load_dwordx2 v[34:35], v[16:17], off offset:1024
	v_add_u32_e32 v16, 1, v12
	v_ashrrev_i32_e32 v17, 31, v16
	v_lshlrev_b64 v[28:29], 11, v[16:17]
	v_lshl_add_u64 v[36:37], v[8:9], 0, v[28:29]
	global_load_dwordx2 v[38:39], v[36:37], off offset:512
	global_load_dwordx2 v[40:41], v[36:37], off
	global_load_dwordx2 v[42:43], v[36:37], off offset:1536
	global_load_dwordx2 v[44:45], v[36:37], off offset:1024
	v_lshlrev_b64 v[16:17], 12, v[16:17]
	s_waitcnt vmcnt(7)
	v_and_b32_e32 v47, 0xffff0000, v18
	s_waitcnt vmcnt(6)
	v_and_b32_e32 v46, 0xffff0000, v20
	s_waitcnt vmcnt(5)
	v_and_b32_e32 v55, 0xffff0000, v32
	s_waitcnt vmcnt(4)
	v_and_b32_e32 v54, 0xffff0000, v34
	v_lshlrev_b32_e32 v53, 16, v32
	v_lshlrev_b32_e32 v52, 16, v34
	v_pk_mul_f32 v[58:59], v[54:55], v[54:55]
	s_waitcnt vmcnt(3)
	v_and_b32_e32 v63, 0xffff0000, v38
	s_waitcnt vmcnt(2)
	v_and_b32_e32 v62, 0xffff0000, v40
	v_lshlrev_b32_e32 v37, 16, v18
	v_lshlrev_b32_e32 v36, 16, v20
	v_lshlrev_b32_e32 v49, 16, v19
	v_lshlrev_b32_e32 v48, 16, v21
	v_and_b32_e32 v51, 0xffff0000, v19
	v_and_b32_e32 v50, 0xffff0000, v21
	v_lshlrev_b32_e32 v56, 16, v35
	v_and_b32_e32 v32, 0xffff0000, v35
	v_pk_mul_f32 v[34:35], v[46:47], v[46:47]
	v_lshlrev_b32_e32 v61, 16, v38
	v_lshlrev_b32_e32 v60, 16, v40
	s_waitcnt vmcnt(1)
	v_lshlrev_b32_e32 v21, 16, v42
	s_waitcnt vmcnt(0)
	v_lshlrev_b32_e32 v20, 16, v44
	v_and_b32_e32 v19, 0xffff0000, v42
	v_and_b32_e32 v18, 0xffff0000, v44
	v_lshlrev_b32_e32 v40, 16, v45
	v_and_b32_e32 v42, 0xffff0000, v45
	v_pk_fma_f32 v[44:45], v[52:53], v[52:53], v[58:59]
	v_pk_mul_f32 v[58:59], v[62:63], v[62:63]
	v_lshlrev_b32_e32 v65, 16, v39
	v_lshlrev_b32_e32 v64, 16, v41
	v_pk_fma_f32 v[34:35], v[36:37], v[36:37], v[34:35]
	v_pk_mul_f32 v[66:67], v[18:19], v[18:19]
	v_pk_fma_f32 v[58:59], v[60:61], v[60:61], v[58:59]
	v_lshlrev_b32_e32 v57, 16, v33
	v_and_b32_e32 v39, 0xffff0000, v39
	v_and_b32_e32 v38, 0xffff0000, v41
	v_lshlrev_b32_e32 v41, 16, v43
	v_pk_fma_f32 v[34:35], v[48:49], v[48:49], v[34:35]
	v_pk_fma_f32 v[66:67], v[20:21], v[20:21], v[66:67]
	v_pk_fma_f32 v[58:59], v[64:65], v[64:65], v[58:59]
	v_and_b32_e32 v33, 0xffff0000, v33
	v_and_b32_e32 v43, 0xffff0000, v43
	v_pk_fma_f32 v[44:45], v[56:57], v[56:57], v[44:45]
	v_pk_fma_f32 v[34:35], v[50:51], v[50:51], v[34:35]
	v_pk_fma_f32 v[66:67], v[40:41], v[40:41], v[66:67]
	v_pk_fma_f32 v[58:59], v[38:39], v[38:39], v[58:59]
	v_pk_fma_f32 v[44:45], v[32:33], v[32:33], v[44:45]
	v_pk_fma_f32 v[66:67], v[42:43], v[42:43], v[66:67]
	v_mov_b32_e32 v69, v34
	v_mov_b32_e32 v68, v58
	v_mov_b32_e32 v34, v59
	v_mov_b32_e32 v71, v44
	v_mov_b32_e32 v70, v66
	v_pk_add_f32 v[34:35], v[68:69], v[34:35]
	v_mov_b32_e32 v44, v67
	v_pk_add_f32 v[34:35], v[34:35], v[70:71]
	v_lshlrev_b64 v[58:59], 12, v[12:13]
	v_pk_add_f32 v[34:35], v[34:35], v[44:45]
	ds_bpermute_b32 v45, v15, v35
	ds_bpermute_b32 v44, v15, v34
	v_mov_b32_e32 v66, v36
	v_mov_b32_e32 v67, v46
	v_lshl_add_u64 v[58:59], v[10:11], 0, v[58:59]
	v_mov_b32_e32 v46, v37
	s_waitcnt lgkmcnt(0)
; DEV void ph_final(const P& p) {
;     ...
; #pragma unroll
;     for (int q = 0; q < 2; ++q) {
;       const float rstd = rsqrtf(ss[q] * (1.0f / 1024.0f) + EPSN);
; #pragma unroll
;       for (int i = 0; i < 4; ++i) { const int col = (lane + 64 * i) * 4; const f32x4 g = *(const f32x4*)(p.norm_final + col); ((f32x4*)(p.out + (size_t)(row0 + q) * 1024))[lane + 64 * i] = v[q][i] * rstd * g; }
;     }
	v_pk_add_f32 v[34:35], v[34:35], v[44:45]
	ds_bpermute_b32 v45, v22, v35
	ds_bpermute_b32 v44, v22, v34
	v_add_u32_e32 v12, s3, v12
	s_waitcnt lgkmcnt(0)
	v_pk_add_f32 v[34:35], v[34:35], v[44:45]
	ds_bpermute_b32 v45, v23, v35
	ds_bpermute_b32 v44, v23, v34
	s_waitcnt lgkmcnt(0)
	v_pk_add_f32 v[34:35], v[34:35], v[44:45]
	ds_bpermute_b32 v45, v24, v35
	ds_bpermute_b32 v44, v24, v34
	s_waitcnt lgkmcnt(0)
	v_pk_add_f32 v[34:35], v[34:35], v[44:45]
	ds_bpermute_b32 v45, v25, v35
	ds_bpermute_b32 v44, v25, v34
	s_waitcnt lgkmcnt(0)
	v_pk_add_f32 v[34:35], v[34:35], v[44:45]
	ds_bpermute_b32 v45, v26, v35
	ds_bpermute_b32 v44, v26, v34
	s_waitcnt lgkmcnt(0)
	v_pk_add_f32 v[34:35], v[34:35], v[44:45]
	s_nop 0
	v_pk_fma_f32 v[34:35], v[34:35], s[0:1], v[14:15] op_sel_hi:[1,0,0]
	v_mov_b32_e32 v44, v48
	v_mul_f32_e32 v13, 0x4b800000, v35
	v_cmp_gt_f32_e32 vcc, s2, v35
	v_mov_b32_e32 v45, v50
	v_mov_b32_e32 v50, v49
	v_cndmask_b32_e32 v13, v35, v13, vcc
	v_rsq_f32_e32 v13, v13
	v_mov_b32_e32 v35, v62
	v_mov_b32_e32 v62, v61
	s_add_i32 s1, s1, s91
	v_mul_f32_e32 v27, 0x45800000, v13
	v_cndmask_b32_e32 v36, v13, v27, vcc
	v_pk_mul_f32 v[66:67], v[36:37], v[66:67] op_sel_hi:[0,1]
	v_pk_mul_f32 v[44:45], v[36:37], v[44:45] op_sel_hi:[0,1]
	v_pk_mul_f32 v[30:31], v[74:75], v[44:45]
	v_pk_mul_f32 v[28:29], v[72:73], v[66:67]
	global_store_dwordx4 v[58:59], v[28:31], off
	v_pk_mul_f32 v[44:45], v[36:37], v[50:51] op_sel_hi:[0,1]
	v_pk_mul_f32 v[46:47], v[36:37], v[46:47] op_sel_hi:[0,1]
	v_mul_f32_e32 v13, 0x4b800000, v34
	v_cmp_gt_f32_e32 vcc, s2, v34
	s_cmpk_lt_i32 s1, 0x1000
	v_pk_mul_f32 v[88:89], v[76:77], v[46:47]
	v_pk_mul_f32 v[90:91], v[78:79], v[44:45]
	global_store_dwordx4 v[58:59], v[88:91], off offset:1024
	v_mov_b32_e32 v44, v56
	v_mov_b32_e32 v45, v32
	v_mov_b32_e32 v46, v52
	v_mov_b32_e32 v47, v54
	v_pk_mul_f32 v[44:45], v[36:37], v[44:45] op_sel_hi:[0,1]
	v_pk_mul_f32 v[46:47], v[36:37], v[46:47] op_sel_hi:[0,1]
	v_mov_b32_e32 v54, v53
	v_mov_b32_e32 v32, v57
	v_pk_mul_f32 v[32:33], v[36:37], v[32:33] op_sel_hi:[0,1]
	v_pk_mul_f32 v[36:37], v[36:37], v[54:55] op_sel_hi:[0,1]
	v_cndmask_b32_e32 v13, v34, v13, vcc
	v_rsq_f32_e32 v13, v13
	v_mov_b32_e32 v34, v60
	v_mul_f32_e32 v27, 0x45800000, v13
	v_pk_mul_f32 v[28:29], v[80:81], v[46:47]
	v_pk_mul_f32 v[30:31], v[82:83], v[44:45]
	global_store_dwordx4 v[58:59], v[28:31], off offset:2048
	v_pk_mul_f32 v[88:89], v[84:85], v[36:37]
	v_pk_mul_f32 v[90:91], v[86:87], v[32:33]
	global_store_dwordx4 v[58:59], v[88:91], off offset:3072
	v_lshl_add_u64 v[32:33], v[10:11], 0, v[16:17]
	v_mov_b32_e32 v16, v64
	v_mov_b32_e32 v17, v38
	v_cndmask_b32_e32 v36, v13, v27, vcc
	v_pk_mul_f32 v[16:17], v[36:37], v[16:17] op_sel_hi:[0,1]
	v_pk_mul_f32 v[34:35], v[36:37], v[34:35] op_sel_hi:[0,1]
	v_mov_b32_e32 v38, v65
	v_pk_mul_f32 v[28:29], v[72:73], v[34:35]
	v_pk_mul_f32 v[30:31], v[74:75], v[16:17]
	global_store_dwordx4 v[32:33], v[28:31], off
	v_pk_mul_f32 v[16:17], v[36:37], v[38:39] op_sel_hi:[0,1]
	v_pk_mul_f32 v[34:35], v[36:37], v[62:63] op_sel_hi:[0,1]
	v_pk_mul_f32 v[88:89], v[76:77], v[34:35]
	v_pk_mul_f32 v[90:91], v[78:79], v[16:17]
	global_store_dwordx4 v[32:33], v[88:91], off offset:1024
	v_mov_b32_e32 v16, v40
	v_mov_b32_e32 v17, v42
	v_mov_b32_e32 v34, v20
	v_mov_b32_e32 v35, v18
	v_pk_mul_f32 v[16:17], v[36:37], v[16:17] op_sel_hi:[0,1]
	v_pk_mul_f32 v[34:35], v[36:37], v[34:35] op_sel_hi:[0,1]
	v_mov_b32_e32 v18, v21
	v_mov_b32_e32 v42, v41
	v_pk_mul_f32 v[20:21], v[36:37], v[42:43] op_sel_hi:[0,1]
	v_pk_mul_f32 v[28:29], v[34:35], v[80:81]
	v_pk_mul_f32 v[30:31], v[16:17], v[82:83]
	global_store_dwordx4 v[32:33], v[28:31], off offset:2048
	v_pk_mul_f32 v[16:17], v[36:37], v[18:19] op_sel_hi:[0,1]
	v_pk_mul_f32 v[16:17], v[16:17], v[84:85]
	v_pk_mul_f32 v[18:19], v[20:21], v[86:87]
	global_store_dwordx4 v[32:33], v[16:19], off offset:3072
	s_cbranch_scc1 .LBB0_1253
